# residual phases: next-row prefetch loads issued back-to-back instead of 8 wait-separated pairs
# speedup vs baseline: 1.0136x; 1.0056x over previous
; __device__ __forceinline__ float bf_lo(unsigned w) { return __uint_as_float(w << 16); }
; __device__ __forceinline__ float bf_hi(unsigned w) { return __uint_as_float(w & 0xffff0000u); }
; __device__ __forceinline__ void phase_resid(const Params& p, const float* g, bool first, bool last, int nsplit) {
;     ...
;         for (;;) {
;             const int nrow = row + nw; const bool more = nrow < MROWS;
;             f32x4 mv2[8], hv2[8];
;             if (more) {
; #pragma unroll
;                 for (int i = 0; i < 8; ++i) { const u32x2 mw = __builtin_nontemporal_load((const u32x2*)(mix + (size_t)nrow * DM + lane * 4 + 256 * i)); mv2[i] = (f32x4){bf_lo(mw.x), bf_hi(mw.x), bf_lo(mw.y), bf_hi(mw.y)}; hv2[i] = *(const f32x4*)(HROW(nrow) + lane * 4 + 256 * i); }
;             }
.LBB0_311:
	v_add_u32_e32 v148, s12, v158
	s_movk_i32 s0, 0x2100
	v_cmp_gt_i32_e64 s[0:1], s0, v148
	s_and_saveexec_b64 s[18:19], s[0:1]
	s_cbranch_execz .LBB0_313
	v_ashrrev_i32_e32 v149, 31, v148
	v_lshlrev_b64 v[34:35], 12, v[148:149]
	v_lshl_add_u64 v[78:79], v[102:103], 0, v[34:35]
	global_load_dwordx2 v[224:225], v[78:79], off nt
	global_load_dwordx2 v[226:227], v[78:79], off offset:512 nt
	global_load_dwordx2 v[228:229], v[78:79], off offset:1024 nt
	global_load_dwordx2 v[230:231], v[78:79], off offset:1536 nt
	global_load_dwordx2 v[232:233], v[78:79], off offset:2048 nt
	global_load_dwordx2 v[234:235], v[78:79], off offset:2560 nt
	global_load_dwordx2 v[236:237], v[78:79], off offset:3072 nt
	global_load_dwordx2 v[238:239], v[78:79], off offset:3584 nt
	s_movk_i32 s3, 0x1000
	v_lshlrev_b64 v[34:35], 13, v[148:149]
	v_lshl_add_u64 v[54:55], v[104:105], 0, v[34:35]
	global_load_dwordx4 v[34:37], v[54:55], off
	v_add_co_u32_e32 v80, vcc, s3, v54
	global_load_dwordx4 v[38:41], v[54:55], off offset:1024
	s_nop 1
	v_addc_co_u32_e32 v81, vcc, 0, v55, vcc
	global_load_dwordx4 v[42:45], v[54:55], off offset:2048
	global_load_dwordx4 v[50:53], v[54:55], off offset:3072
	global_load_dwordx4 v[54:57], v[80:81], off
	global_load_dwordx4 v[62:65], v[80:81], off offset:1024
	global_load_dwordx4 v[70:73], v[80:81], off offset:2048
	s_nop 0
	global_load_dwordx4 v[78:81], v[80:81], off offset:3072
	s_waitcnt vmcnt(8)
	v_lshlrev_b32_e32 v159, 16, v224
	v_and_b32_e32 v160, 0xffff0000, v224
	v_lshlrev_b32_e32 v161, 16, v225
	v_and_b32_e32 v162, 0xffff0000, v225
	v_lshlrev_b32_e32 v163, 16, v226
	v_and_b32_e32 v164, 0xffff0000, v226
	v_lshlrev_b32_e32 v165, 16, v227
	v_and_b32_e32 v166, 0xffff0000, v227
	v_lshlrev_b32_e32 v167, 16, v228
	v_and_b32_e32 v168, 0xffff0000, v228
	v_lshlrev_b32_e32 v169, 16, v229
	v_and_b32_e32 v170, 0xffff0000, v229
	v_lshlrev_b32_e32 v171, 16, v230
	v_and_b32_e32 v172, 0xffff0000, v230
	v_lshlrev_b32_e32 v173, 16, v231
	v_and_b32_e32 v174, 0xffff0000, v231
	v_lshlrev_b32_e32 v175, 16, v232
	v_and_b32_e32 v176, 0xffff0000, v232
	v_lshlrev_b32_e32 v177, 16, v233
	v_and_b32_e32 v178, 0xffff0000, v233
	v_lshlrev_b32_e32 v179, 16, v234
	v_and_b32_e32 v180, 0xffff0000, v234
	v_lshlrev_b32_e32 v181, 16, v235
	v_and_b32_e32 v182, 0xffff0000, v235
	v_lshlrev_b32_e32 v183, 16, v236
	v_and_b32_e32 v184, 0xffff0000, v236
	v_lshlrev_b32_e32 v185, 16, v237
	v_and_b32_e32 v186, 0xffff0000, v237
	v_lshlrev_b32_e32 v187, 16, v238
	v_and_b32_e32 v188, 0xffff0000, v238
	v_lshlrev_b32_e32 v189, 16, v239
	v_and_b32_e32 v190, 0xffff0000, v239

; __device__ __forceinline__ float bf_lo(unsigned w) { return __uint_as_float(w << 16); }
; __device__ __forceinline__ float bf_hi(unsigned w) { return __uint_as_float(w & 0xffff0000u); }
; __device__ __forceinline__ void phase_resid(const Params& p, const float* g, bool first, bool last, int nsplit) {
;     ...
;         for (int i = 0; i < 8; ++i) { const u32x2 mw = __builtin_nontemporal_load((const u32x2*)(mix + (size_t)row * DM + lane * 4 + 256 * i)); mv[i] = (f32x4){bf_lo(mw.x), bf_hi(mw.x), bf_lo(mw.y), bf_hi(mw.y)}; hv[i] = *(const f32x4*)(HROW(row) + lane * 4 + 256 * i); }
;         for (;;) {
;             const int nrow = row + nw; const bool more = nrow < MROWS;
;             f32x4 mv2[8], hv2[8];
;             if (more) {
; #pragma unroll
;                 for (int i = 0; i < 8; ++i) { const u32x2 mw = __builtin_nontemporal_load((const u32x2*)(mix + (size_t)nrow * DM + lane * 4 + 256 * i)); mv2[i] = (f32x4){bf_lo(mw.x), bf_hi(mw.x), bf_lo(mw.y), bf_hi(mw.y)}; hv2[i] = *(const f32x4*)(HROW(nrow) + lane * 4 + 256 * i); }
;             }
.LBB0_773:
	s_movk_i32 s2, 0x2100
	v_cmp_gt_i32_e32 vcc, s2, v106
	s_and_saveexec_b64 s[18:19], vcc
	s_cbranch_execz .LBB0_775
	v_add_u32_e32 v50, 0xffffff10, v106
	v_ashrrev_i32_e32 v107, 31, v106
	v_add_u32_e32 v0, 0xffffff00, v106
	v_ashrrev_i32_e32 v51, 31, v50
	v_lshlrev_b64 v[34:35], 12, v[106:107]
	s_movk_i32 s2, 0x100
	v_lshlrev_b64 v[36:37], 13, v[0:1]
	v_lshlrev_b64 v[50:51], 13, v[50:51]
	s_waitcnt vmcnt(16)
	v_lshl_add_u64 v[94:95], v[104:105], 0, v[34:35]
	v_lshlrev_b64 v[34:35], 13, v[106:107]
	v_cmp_gt_i32_e64 s[4:5], s2, v106
	v_lshl_add_u64 v[36:37], s[38:39], 0, v[36:37]
	v_lshl_add_u64 v[50:51], s[40:41], 0, v[50:51]
	v_lshl_add_u64 v[34:35], s[8:9], 0, v[34:35]
	v_cndmask_b32_e64 v36, v36, v50, s[4:5]
	v_cndmask_b32_e64 v37, v37, v51, s[4:5]
	v_cndmask_b32_e64 v35, v35, v37, s[0:1]
	v_cndmask_b32_e64 v34, v34, v36, s[0:1]
	v_mov_b32_e32 v99, v1
	v_lshl_add_u64 v[78:79], v[34:35], 0, v[98:99]
	global_load_dwordx2 v[224:225], v[94:95], off nt
	global_load_dwordx2 v[226:227], v[94:95], off offset:512 nt
	global_load_dwordx2 v[228:229], v[94:95], off offset:1024 nt
	global_load_dwordx2 v[230:231], v[94:95], off offset:1536 nt
	global_load_dwordx2 v[232:233], v[94:95], off offset:2048 nt
	global_load_dwordx2 v[234:235], v[94:95], off offset:2560 nt
	global_load_dwordx2 v[236:237], v[94:95], off offset:3072 nt
	global_load_dwordx2 v[238:239], v[94:95], off offset:3584 nt
	global_load_dwordx4 v[34:37], v[78:79], off
	s_movk_i32 s2, 0x1000
	v_add_co_u32_e64 v96, s[4:5], s2, v78
	global_load_dwordx4 v[50:53], v[78:79], off offset:1024
	s_nop 1
	v_addc_co_u32_e64 v97, s[4:5], 0, v79, s[4:5]
	global_load_dwordx4 v[58:61], v[78:79], off offset:2048
	global_load_dwordx4 v[66:69], v[78:79], off offset:3072
	global_load_dwordx4 v[78:81], v[96:97], off
	global_load_dwordx4 v[86:89], v[96:97], off offset:1024
	global_load_dwordx4 v[90:93], v[96:97], off offset:2048
	s_nop 0
	global_load_dwordx4 v[94:97], v[96:97], off offset:3072
	s_waitcnt vmcnt(8)
	v_lshlrev_b32_e32 v0, 16, v224
	v_and_b32_e32 v107, 0xffff0000, v224
	v_lshlrev_b32_e32 v140, 16, v225
	v_and_b32_e32 v147, 0xffff0000, v225
	v_lshlrev_b32_e32 v99, 16, v226
	v_and_b32_e32 v148, 0xffff0000, v226
	v_lshlrev_b32_e32 v149, 16, v227
	v_and_b32_e32 v150, 0xffff0000, v227
	v_lshlrev_b32_e32 v151, 16, v228
	v_and_b32_e32 v152, 0xffff0000, v228
	v_lshlrev_b32_e32 v153, 16, v229
	v_and_b32_e32 v154, 0xffff0000, v229
	v_lshlrev_b32_e32 v155, 16, v230
	v_and_b32_e32 v156, 0xffff0000, v230
	v_lshlrev_b32_e32 v157, 16, v231
	v_and_b32_e32 v158, 0xffff0000, v231
	v_lshlrev_b32_e32 v159, 16, v232
	v_and_b32_e32 v160, 0xffff0000, v232
	v_lshlrev_b32_e32 v161, 16, v233
	v_and_b32_e32 v162, 0xffff0000, v233
	v_lshlrev_b32_e32 v163, 16, v234
	v_and_b32_e32 v164, 0xffff0000, v234
	v_lshlrev_b32_e32 v165, 16, v235
	v_and_b32_e32 v166, 0xffff0000, v235
	v_lshlrev_b32_e32 v167, 16, v236
	v_and_b32_e32 v168, 0xffff0000, v236
	v_lshlrev_b32_e32 v169, 16, v237
	v_and_b32_e32 v170, 0xffff0000, v237
	v_lshlrev_b32_e32 v171, 16, v238
	v_and_b32_e32 v172, 0xffff0000, v238
	v_lshlrev_b32_e32 v173, 16, v239
	v_and_b32_e32 v174, 0xffff0000, v239
